# P0 tconv instances 2,3,4 (w_in_a idx cols, w_out_a, w_in_b z): batched tile loads
# speedup vs baseline: 1.0268x; 1.0139x over previous
;     ...
;     { const int c = tid & 63, r = tid >> 6; const int sc0 = cm(np * 128 + c), sc1 = cm(np * 128 + 64 + c);
;       float v0[8], v1[8];
; #pragma unroll
;       for (int pass = 0; pass < 8; ++pass) { const int k = kt * 64 + pass * 8 + r; const float g = (gk ? gk[k] : 1.f) * wsc;
;         v0[pass] = (sc0 >= 0) ? src[(size_t)k * ldS + sc0] * g : 0.f; v1[pass] = (sc1 >= 0) ? src[(size_t)k * ldS + sc1] * g : 0.f; }
;   int tid = threadIdx.x; asm volatile("" : "+v"(tid));
;   const int Np = Ntiles >> 1;
;   for (int tile = bid; tile < Ktiles * Np; tile += nb) tconv_tile<CM, FP8>(dst, ldD, src, ldS, tile / Np, tile % Np, gk, cm, tl, tid, wsc);
.LBB0_158:
	s_lshl_b32 s8, s20, 6
	v_add_u32_e32 v10, s8, v5
	v_ashrrev_i32_e32 v11, 31, v10
	v_readlane_b32 s38, v254, 2
	v_readlane_b32 s39, v254, 3
	v_readlane_b32 s40, v254, 4
	v_readlane_b32 s41, v254, 5
	v_cmp_lt_i32_e64 s[4:5], -1, v6
	v_cmp_lt_i32_e64 s[6:7], -1, v14
	s_mov_b32 s72, 0x4aa00
	s_mov_b32 s73, 0
	v_lshl_add_u64 v[50:51], v[10:11], 2, s[38:39]
	global_load_dword v52, v[50:51], off
	global_load_dword v53, v[50:51], off offset:32
	global_load_dword v54, v[50:51], off offset:64
	global_load_dword v55, v[50:51], off offset:96
	global_load_dword v56, v[50:51], off offset:128
	global_load_dword v57, v[50:51], off offset:160
	global_load_dword v58, v[50:51], off offset:192
	global_load_dword v59, v[50:51], off offset:224
	v_lshl_add_u64 v[12:13], v[6:7], 2, s[40:41]
	v_mov_b32_e32 v15, v7
	v_lshl_add_u64 v[14:15], v[14:15], 2, s[40:41]
	v_mad_i64_i32 v[12:13], s[36:37], v10, s33, v[12:13]
	v_mad_i64_i32 v[14:15], s[36:37], v10, s33, v[14:15]
	v_mov_b32_e32 v20, 0
	v_mov_b32_e32 v23, 0
	v_mov_b32_e32 v25, 0
	v_mov_b32_e32 v27, 0
	v_mov_b32_e32 v29, 0
	v_mov_b32_e32 v31, 0
	v_mov_b32_e32 v33, 0
	v_mov_b32_e32 v11, 0
	v_mov_b32_e32 v6, 0
	v_mov_b32_e32 v21, 0
	v_mov_b32_e32 v24, 0
	v_mov_b32_e32 v26, 0
	v_mov_b32_e32 v28, 0
	v_mov_b32_e32 v30, 0
	v_mov_b32_e32 v32, 0
	v_mov_b32_e32 v10, 0
	s_mov_b64 s[20:21], exec
	s_and_b64 exec, s[20:21], s[4:5]
	global_load_dword v20, v[12:13], off
	v_lshl_add_u64 v[12:13], v[12:13], 0, s[72:73]
	global_load_dword v23, v[12:13], off
	v_lshl_add_u64 v[12:13], v[12:13], 0, s[72:73]
	global_load_dword v25, v[12:13], off
	v_lshl_add_u64 v[12:13], v[12:13], 0, s[72:73]
	global_load_dword v27, v[12:13], off
	v_lshl_add_u64 v[12:13], v[12:13], 0, s[72:73]
	global_load_dword v29, v[12:13], off
	v_lshl_add_u64 v[12:13], v[12:13], 0, s[72:73]
	global_load_dword v31, v[12:13], off
	v_lshl_add_u64 v[12:13], v[12:13], 0, s[72:73]
	global_load_dword v33, v[12:13], off
	v_lshl_add_u64 v[12:13], v[12:13], 0, s[72:73]
	global_load_dword v11, v[12:13], off
	s_and_b64 exec, s[20:21], s[6:7]
	global_load_dword v6, v[14:15], off
	v_lshl_add_u64 v[14:15], v[14:15], 0, s[72:73]
	global_load_dword v21, v[14:15], off
	v_lshl_add_u64 v[14:15], v[14:15], 0, s[72:73]
	global_load_dword v24, v[14:15], off
	v_lshl_add_u64 v[14:15], v[14:15], 0, s[72:73]
	global_load_dword v26, v[14:15], off
	v_lshl_add_u64 v[14:15], v[14:15], 0, s[72:73]
	global_load_dword v28, v[14:15], off
	v_lshl_add_u64 v[14:15], v[14:15], 0, s[72:73]
	global_load_dword v30, v[14:15], off
	v_lshl_add_u64 v[14:15], v[14:15], 0, s[72:73]
	global_load_dword v32, v[14:15], off
	v_lshl_add_u64 v[14:15], v[14:15], 0, s[72:73]
	global_load_dword v10, v[14:15], off
	s_mov_b64 exec, s[20:21]
	s_waitcnt vmcnt(0)
	v_mul_f32_e32 v20, v52, v20
	v_mul_f32_e32 v6, v52, v6
	v_mul_f32_e32 v23, v53, v23
	v_mul_f32_e32 v21, v53, v21
	v_mul_f32_e32 v25, v54, v25
	v_mul_f32_e32 v24, v54, v24
	v_mul_f32_e32 v27, v55, v27
	v_mul_f32_e32 v26, v55, v26
	v_mul_f32_e32 v29, v56, v29
	v_mul_f32_e32 v28, v56, v28
	v_mul_f32_e32 v31, v57, v31
	v_mul_f32_e32 v30, v57, v30
	v_mul_f32_e32 v33, v58, v33
	v_mul_f32_e32 v32, v58, v32
	v_mul_f32_e32 v11, v59, v11
	v_mul_f32_e32 v10, v59, v10
	s_branch .LBB0_121
.LBB0_214:
	s_cmpk_lt_i32 s88, 0x400
	v_mov_b32_e32 v6, v200
	s_cselect_b64 s[4:5], -1, 0
	s_cmpk_gt_i32 s88, 0x3ff
	s_cbranch_scc1 .LBB0_250
	v_and_b32_e32 v3, 63, v6
	v_ashrrev_i32_e32 v5, 6, v6
	s_movk_i32 s0, 0x204
	v_lshlrev_b32_e32 v7, 2, v3
	v_mul_lo_u32 v8, v5, s0
	v_ashrrev_i32_e32 v18, 3, v6
	v_lshlrev_b32_e32 v6, 3, v6
	v_readlane_b32 s0, v254, 16
	v_add3_u32 v16, 0, v7, v8
	v_add3_u32 v17, 0, v8, v7
	v_and_b32_e32 v6, 56, v6
	v_mov_b32_e32 v7, 0
	v_readlane_b32 s1, v254, 17
	v_readlane_b32 s2, v254, 18
	v_readlane_b32 s3, v254, 19
	s_mov_b64 s[0:1], 0x30000000
	v_lshl_add_u32 v10, v18, 2, 0
	v_lshl_add_u64 v[8:9], s[2:3], 0, v[6:7]
	v_mul_u32_u24_e32 v6, 0x204, v6
	v_lshl_add_u64 v[8:9], v[8:9], 0, s[0:1]
	s_lshl_b32 s2, s88, 7
	s_lshl_b32 s3, s89, 7
	v_add_u32_e32 v19, v10, v6
	s_mov_b32 s20, s88
	s_branch .LBB0_218
;     ...
;     { const int c = tid & 63, r = tid >> 6; const int sc0 = cm(np * 128 + c), sc1 = cm(np * 128 + 64 + c);
;       float v0[8], v1[8];
; #pragma unroll
;       for (int pass = 0; pass < 8; ++pass) { const int k = kt * 64 + pass * 8 + r; const float g = (gk ? gk[k] : 1.f) * wsc;
;         v0[pass] = (sc0 >= 0) ? src[(size_t)k * ldS + sc0] * g : 0.f; v1[pass] = (sc1 >= 0) ? src[(size_t)k * ldS + sc1] * g : 0.f; }
; #pragma unroll
;       for (int pass = 0; pass < 8; ++pass) { tl[(pass * 8 + r) * 129 + c] = v0[pass]; tl[(pass * 8 + r) * 129 + 64 + c] = v1[pass]; } }
;     __syncthreads();
; #pragma unroll
;     for (int hf = 0; hf < 2; ++hf) { const int nl = hf * 64 + (tid >> 3), kc = tid & 7; float v[8];
; #pragma unroll
;       for (int j = 0; j < 8; ++j) v[j] = tl[(kc * 8 + j) * 129 + nl];
;       if constexpr (FP8) {
;         u32x2 w; w[0] = __builtin_amdgcn_cvt_pk_fp8_f32(v[0], v[1], 0, false); w[0] = __builtin_amdgcn_cvt_pk_fp8_f32(v[2], v[3], w[0], true);
;         w[1] = __builtin_amdgcn_cvt_pk_fp8_f32(v[4], v[5], 0, false); w[1] = __builtin_amdgcn_cvt_pk_fp8_f32(v[6], v[7], w[1], true);
;         *(u32x2*)((unsigned char*)dst + (size_t)(np * 128 + nl) * ldD + kt * 64 + kc * 8) = w;
.LBB0_217:
	ds_write_b32 v16, v6
	ds_write_b32 v17, v21 offset:256
	ds_write_b32 v16, v20 offset:4128
	ds_write_b32 v17, v24 offset:4384
	ds_write_b32 v16, v23 offset:8256
	ds_write_b32 v17, v26 offset:8512
	ds_write_b32 v16, v25 offset:12384
	ds_write_b32 v17, v28 offset:12640
	ds_write_b32 v16, v27 offset:16512
	ds_write_b32 v17, v30 offset:16768
	ds_write_b32 v16, v29 offset:20640
	ds_write_b32 v17, v32 offset:20896
	ds_write_b32 v16, v31 offset:24768
	ds_write_b32 v17, v34 offset:25024
	ds_write_b32 v16, v33 offset:28896
	ds_write_b32 v17, v10 offset:29152
	v_add_u32_e32 v6, 8, v19
	s_waitcnt lgkmcnt(0)
	s_barrier
	ds_read2st64_b32 v[10:11], v19 offset1:1
	ds_read2_b32 v[12:13], v19 offset0:129 offset1:193
	ds_read2st64_b32 v[14:15], v6 offset0:4 offset1:5
	v_add_u32_e32 v6, 12, v19
	ds_read2st64_b32 v[20:21], v6 offset0:6 offset1:7
	v_add_u32_e32 v6, 16, v19
	ds_read2st64_b32 v[24:25], v6 offset0:8 offset1:9
	v_add_u32_e32 v6, 20, v19
	ds_read2st64_b32 v[26:27], v6 offset0:10 offset1:11
	v_add_u32_e32 v6, 24, v19
	ds_read2st64_b32 v[28:29], v6 offset0:12 offset1:13
	v_add_u32_e32 v6, 28, v19
	ds_read2st64_b32 v[30:31], v6 offset0:14 offset1:15
	v_mov_b32_e32 v32, v7
	v_mov_b32_e32 v33, v7
	s_waitcnt lgkmcnt(6)
	v_cvt_pk_fp8_f32 v32, v10, v12
	s_waitcnt lgkmcnt(2)
	v_cvt_pk_fp8_f32 v33, v24, v26
	s_sub_i32 s0, 0, s7
	v_mov_b32_e32 v10, v7
	s_add_i32 s0, s0, s2
	v_cvt_pk_fp8_f32 v10, v11, v13
	v_mov_b32_e32 v11, v7
	v_cvt_pk_fp8_f32 v32, v14, v20 op_sel:[0,0,1]
	s_waitcnt lgkmcnt(0)
	v_cvt_pk_fp8_f32 v33, v28, v30 op_sel:[0,0,1]
	v_add_u32_e32 v36, s0, v18
	v_cvt_pk_fp8_f32 v11, v25, v27
	s_ashr_i32 s7, s6, 31
	v_ashrrev_i32_e32 v37, 31, v36
	v_lshl_add_u64 v[34:35], v[8:9], 0, s[6:7]
	v_lshlrev_b64 v[38:39], 12, v[36:37]
	v_lshl_add_u64 v[12:13], v[34:35], 0, v[38:39]
	global_store_dwordx2 v[12:13], v[32:33], off
	v_cvt_pk_fp8_f32 v10, v15, v21 op_sel:[0,0,1]
	v_cvt_pk_fp8_f32 v11, v29, v31 op_sel:[0,0,1]
	v_add_u32_e32 v12, 64, v36
	v_ashrrev_i32_e32 v13, 31, v12
	v_lshlrev_b64 v[12:13], 12, v[12:13]
	s_add_i32 s20, s20, s89
	s_add_i32 s2, s2, s3
	v_lshl_add_u64 v[12:13], v[34:35], 0, v[12:13]
	s_cmpk_lt_i32 s20, 0x400
	global_store_dwordx2 v[12:13], v[10:11], off
	s_barrier
	s_cbranch_scc0 .LBB0_250
.LBB0_218:
	s_ashr_i32 s0, s20, 31
	s_lshr_b32 s0, s0, 28
	s_add_i32 s0, s20, s0
	s_ashr_i32 s1, s0, 4
	s_lshl_b32 s7, s1, 11
	s_and_b32 s0, s0, -16
	s_sub_i32 s6, s2, s7
	s_sub_i32 s0, s20, s0
	v_add_u32_e32 v6, s6, v3
	s_lshl_b32 s6, s1, 6
	v_readlane_b32 s36, v254, 0
	v_add_u32_e32 v12, s6, v5
	s_cmp_gt_i32 s0, -1
	v_readlane_b32 s50, v254, 14
	v_readlane_b32 s51, v254, 15
	s_cselect_b64 s[8:9], -1, 0
	s_cmp_lt_i32 s0, 0
	v_lshl_add_u64 v[10:11], v[6:7], 2, s[50:51]
	v_ashrrev_i32_e32 v13, 31, v12
	v_mov_b32_e32 v6, 0
	v_readlane_b32 s37, v254, 1
	v_readlane_b32 s38, v254, 2
	v_readlane_b32 s39, v254, 3
	v_readlane_b32 s40, v254, 4
	v_readlane_b32 s41, v254, 5
	v_readlane_b32 s42, v254, 6
	v_readlane_b32 s43, v254, 7
	v_readlane_b32 s44, v254, 8
	v_readlane_b32 s45, v254, 9
	v_readlane_b32 s46, v254, 10
	v_readlane_b32 s47, v254, 11
	v_readlane_b32 s48, v254, 12
	v_readlane_b32 s49, v254, 13
	v_lshlrev_b64 v[14:15], 13, v[12:13]
	v_lshl_add_u64 v[14:15], v[10:11], 0, v[14:15]
	s_mov_b32 s72, 0x10000
	s_mov_b32 s73, 0
	global_load_dword v6, v[14:15], off
	global_load_dword v21, v[14:15], off offset:256
	v_lshl_add_u64 v[14:15], v[14:15], 0, s[72:73]
	global_load_dword v20, v[14:15], off
	global_load_dword v24, v[14:15], off offset:256
	v_lshl_add_u64 v[14:15], v[14:15], 0, s[72:73]
	global_load_dword v23, v[14:15], off
	global_load_dword v26, v[14:15], off offset:256
	v_lshl_add_u64 v[14:15], v[14:15], 0, s[72:73]
	global_load_dword v25, v[14:15], off
	global_load_dword v28, v[14:15], off offset:256
	v_lshl_add_u64 v[14:15], v[14:15], 0, s[72:73]
	global_load_dword v27, v[14:15], off
	global_load_dword v30, v[14:15], off offset:256
	v_lshl_add_u64 v[14:15], v[14:15], 0, s[72:73]
	global_load_dword v29, v[14:15], off
	global_load_dword v32, v[14:15], off offset:256
	v_lshl_add_u64 v[14:15], v[14:15], 0, s[72:73]
	global_load_dword v31, v[14:15], off
	global_load_dword v34, v[14:15], off offset:256
	v_lshl_add_u64 v[14:15], v[14:15], 0, s[72:73]
	global_load_dword v33, v[14:15], off
	global_load_dword v10, v[14:15], off offset:256
	s_waitcnt vmcnt(0)
	v_mul_f32_e32 v6, 0x42800000, v6
	v_mul_f32_e32 v21, 0x42800000, v21
	v_mul_f32_e32 v20, 0x42800000, v20
	v_mul_f32_e32 v24, 0x42800000, v24
	v_mul_f32_e32 v23, 0x42800000, v23
	v_mul_f32_e32 v26, 0x42800000, v26
	v_mul_f32_e32 v25, 0x42800000, v25
	v_mul_f32_e32 v28, 0x42800000, v28
	v_mul_f32_e32 v27, 0x42800000, v27
	v_mul_f32_e32 v30, 0x42800000, v30
	v_mul_f32_e32 v29, 0x42800000, v29
	v_mul_f32_e32 v32, 0x42800000, v32
	v_mul_f32_e32 v31, 0x42800000, v31
	v_mul_f32_e32 v34, 0x42800000, v34
	v_mul_f32_e32 v33, 0x42800000, v33
	v_mul_f32_e32 v10, 0x42800000, v10
	s_branch .LBB0_217

;     ...
;     { const int c = tid & 63, r = tid >> 6; const int sc0 = cm(np * 128 + c), sc1 = cm(np * 128 + 64 + c);
;       float v0[8], v1[8];
; #pragma unroll
;       for (int pass = 0; pass < 8; ++pass) { const int k = kt * 64 + pass * 8 + r; const float g = (gk ? gk[k] : 1.f) * wsc;
;         v0[pass] = (sc0 >= 0) ? src[(size_t)k * ldS + sc0] * g : 0.f; v1[pass] = (sc1 >= 0) ? src[(size_t)k * ldS + sc1] * g : 0.f; }
; __device__ __forceinline__ void p0_prep(const Params& p, unsigned char* lds, int bid, int nb) {
;     ...
;   tconv((bf16_t*)(ws + OFF_WB) + (size_t)4096 * LDWB, LDWB, p.w_in_b, 8192, 32, 64, p.norm_b, CmOff{4096}, tl, bid, nb);
.LBB0_253:
	s_ashr_i32 s6, s36, 31
	s_lshr_b32 s6, s6, 27
	s_add_i32 s6, s36, s6
	s_ashr_i32 s6, s6, 5
	s_lshl_b32 s24, s6, 6
	v_add_u32_e32 v8, s24, v5
	v_ashrrev_i32_e32 v9, 31, v8
	v_lshl_add_u64 v[50:51], v[8:9], 2, s[12:13]
	global_load_dword v52, v[50:51], off
	global_load_dword v53, v[50:51], off offset:32
	global_load_dword v54, v[50:51], off offset:64
	global_load_dword v55, v[50:51], off offset:96
	global_load_dword v56, v[50:51], off offset:128
	global_load_dword v57, v[50:51], off offset:160
	global_load_dword v58, v[50:51], off offset:192
	global_load_dword v59, v[50:51], off offset:224
	s_lshl_b32 s25, s6, 12
	s_sub_i32 s6, s2, s25
	v_add_u32_e32 v12, s6, v3
	v_ashrrev_i32_e32 v13, 31, v12
	v_lshl_add_u64 v[14:15], v[12:13], 2, s[14:15]
	v_cmp_lt_i32_e64 s[6:7], s33, v12
	v_cmp_lt_i32_e64 s[8:9], s34, v12
	v_lshl_add_u64 v[10:11], v[14:15], 0, s[0:1]
	v_lshl_add_u64 v[12:13], v[14:15], 0, s[20:21]
	v_lshlrev_b64 v[60:61], 15, v[8:9]
	v_lshl_add_u64 v[10:11], v[10:11], 0, v[60:61]
	v_lshl_add_u64 v[12:13], v[12:13], 0, v[60:61]
	s_mov_b32 s72, 0x40000
	s_mov_b32 s73, 0
	v_mov_b32_e32 v21, 0
	v_mov_b32_e32 v24, 0
	v_mov_b32_e32 v26, 0
	v_mov_b32_e32 v28, 0
	v_mov_b32_e32 v30, 0
	v_mov_b32_e32 v32, 0
	v_mov_b32_e32 v34, 0
	v_mov_b32_e32 v15, 0
	v_mov_b32_e32 v20, 0
	v_mov_b32_e32 v23, 0
	v_mov_b32_e32 v25, 0
	v_mov_b32_e32 v27, 0
	v_mov_b32_e32 v29, 0
	v_mov_b32_e32 v31, 0
	v_mov_b32_e32 v33, 0
	v_mov_b32_e32 v14, 0
	s_mov_b64 s[26:27], exec
	s_and_b64 exec, s[26:27], s[6:7]
	global_load_dword v21, v[10:11], off
	v_lshl_add_u64 v[10:11], v[10:11], 0, s[72:73]
	global_load_dword v24, v[10:11], off
	v_lshl_add_u64 v[10:11], v[10:11], 0, s[72:73]
	global_load_dword v26, v[10:11], off
	v_lshl_add_u64 v[10:11], v[10:11], 0, s[72:73]
	global_load_dword v28, v[10:11], off
	v_lshl_add_u64 v[10:11], v[10:11], 0, s[72:73]
	global_load_dword v30, v[10:11], off
	v_lshl_add_u64 v[10:11], v[10:11], 0, s[72:73]
	global_load_dword v32, v[10:11], off
	v_lshl_add_u64 v[10:11], v[10:11], 0, s[72:73]
	global_load_dword v34, v[10:11], off
	v_lshl_add_u64 v[10:11], v[10:11], 0, s[72:73]
	global_load_dword v15, v[10:11], off
	s_and_b64 exec, s[26:27], s[8:9]
	global_load_dword v20, v[12:13], off
	v_lshl_add_u64 v[12:13], v[12:13], 0, s[72:73]
	global_load_dword v23, v[12:13], off
	v_lshl_add_u64 v[12:13], v[12:13], 0, s[72:73]
	global_load_dword v25, v[12:13], off
	v_lshl_add_u64 v[12:13], v[12:13], 0, s[72:73]
	global_load_dword v27, v[12:13], off
	v_lshl_add_u64 v[12:13], v[12:13], 0, s[72:73]
	global_load_dword v29, v[12:13], off
	v_lshl_add_u64 v[12:13], v[12:13], 0, s[72:73]
	global_load_dword v31, v[12:13], off
	v_lshl_add_u64 v[12:13], v[12:13], 0, s[72:73]
	global_load_dword v33, v[12:13], off
	v_lshl_add_u64 v[12:13], v[12:13], 0, s[72:73]
	global_load_dword v14, v[12:13], off
	s_mov_b64 exec, s[26:27]
	s_waitcnt vmcnt(0)
	v_mul_f32_e32 v21, v52, v21
	v_mul_f32_e32 v20, v52, v20
	v_mul_f32_e32 v24, v53, v24
	v_mul_f32_e32 v23, v53, v23
	v_mul_f32_e32 v26, v54, v26
	v_mul_f32_e32 v25, v54, v25
	v_mul_f32_e32 v28, v55, v28
	v_mul_f32_e32 v27, v55, v27
	v_mul_f32_e32 v30, v56, v30
	v_mul_f32_e32 v29, v56, v29
	v_mul_f32_e32 v32, v57, v32
	v_mul_f32_e32 v31, v57, v31
	v_mul_f32_e32 v34, v58, v34
	v_mul_f32_e32 v33, v58, v33
	v_mul_f32_e32 v15, v59, v15
	v_mul_f32_e32 v14, v59, v14
	s_branch .LBB0_252
